# speedup vs baseline: 1.0061x; 1.0061x over previous
.LBB0_372:
	s_cmp_ge_i32 s40, s18
	s_cselect_b64 s[6:7], -1, 0
	s_and_b64 vcc, s[6:7], exec
	s_cselect_b32 s8, s18, 0
	s_sub_i32 s8, s40, s8
	v_lshl_or_b32 v138, s8, 8, v162
	s_movk_i32 s8, 0x200
	v_lshl_add_u32 v140, s42, 8, v160
	v_cmp_gt_i32_e64 s[40:41], s8, v138
	v_readlane_b32 s8, v236, 16
	v_ashrrev_i32_e32 v141, 31, v140
	v_readlane_b32 s9, v236, 17
	s_movk_i32 s12, 0x1800
	s_nop 0
	v_lshl_add_u64 v[142:143], v[140:141], 3, s[8:9]
	global_load_dwordx2 v[144:145], v[142:143], off
	global_load_dwordx2 v[242:243], v[142:143], off offset:128
	global_load_dwordx2 v[244:245], v[142:143], off offset:256
	global_load_dwordx2 v[246:247], v[142:143], off offset:384
	global_load_dwordx2 v[248:249], v[142:143], off offset:1024
	global_load_dwordx2 v[250:251], v[142:143], off offset:1152
	global_load_dwordx2 v[252:253], v[142:143], off offset:1280
	global_load_dwordx2 v[254:255], v[142:143], off offset:1408
	v_mad_i64_i32 v[148:149], s[8:9], v140, s12, 0
	s_mov_b64 s[8:9], -1
	v_lshl_add_u64 v[146:147], s[66:67], 0, v[148:149]
	s_waitcnt vmcnt(0)
	v_ffbh_u32_e32 v128, v145
	v_min_u32_e32 v128, 32, v128
	v_lshlrev_b64 v[144:145], v128, v[144:145]
	v_min_u32_e32 v139, 1, v144
	v_or_b32_e32 v139, v145, v139
	v_cvt_f32_u32_e32 v139, v139
	v_sub_u32_e32 v128, 32, v128
	v_ldexp_f32 v128, v139, v128
	v_fmamk_f32 v128, v128, 0x2e000000, v191
	v_cmp_gt_f32_e64 s[42:43], s58, v128
	s_cbranch_vccz .LBB0_374
	v_lshl_add_u64 v[158:159], s[66:67], 0, v[148:149]
	s_mov_b64 s[8:9], 0

.LBB0_388:
	s_nop 1
	v_cvt_pk_bf16_f32 v112, v112, v113
	v_cvt_pk_bf16_f32 v113, v114, v115
	v_lshl_add_u64 v[114:115], v[138:139], 1, v[146:147]
	global_store_dwordx2 v[114:115], v[112:113], off offset:288
	v_or_b32_e32 v114, 16, v140
	v_mad_i64_i32 v[146:147], s[8:9], v114, s12, 0
	s_mov_b64 s[6:7], -1
	s_and_b64 vcc, exec, s[40:41]
	s_nop 1
	v_ffbh_u32_e32 v115, v243
	v_min_u32_e32 v115, 32, v115
	v_lshlrev_b64 v[112:113], v115, v[242:243]
	v_min_u32_e32 v112, 1, v112
	v_or_b32_e32 v112, v113, v112
	v_cvt_f32_u32_e32 v112, v112
	v_sub_u32_e32 v113, 32, v115
	v_ldexp_f32 v112, v112, v113
	v_fmamk_f32 v115, v112, 0x2e000000, v191
	v_cmp_gt_f32_e64 s[42:43], s58, v115
	v_lshl_add_u64 v[112:113], s[66:67], 0, v[146:147]
	s_cbranch_vccnz .LBB0_390
	v_lshl_add_u64 v[148:149], s[66:67], 0, v[146:147]
	s_mov_b64 s[6:7], 0

.LBB0_404:
	s_nop 1
	v_cvt_pk_bf16_f32 v96, v96, v97
	v_cvt_pk_bf16_f32 v97, v98, v99
	v_lshl_add_u64 v[98:99], v[138:139], 1, v[112:113]
	global_store_dwordx2 v[98:99], v[96:97], off offset:288
	v_or_b32_e32 v98, 32, v140
	v_mad_i64_i32 v[106:107], s[8:9], v98, s12, 0
	s_mov_b64 s[6:7], -1
	s_and_b64 vcc, exec, s[40:41]
	s_nop 1
	v_ffbh_u32_e32 v99, v245
	v_min_u32_e32 v99, 32, v99
	v_lshlrev_b64 v[96:97], v99, v[244:245]
	v_min_u32_e32 v96, 1, v96
	v_or_b32_e32 v96, v97, v96
	v_cvt_f32_u32_e32 v96, v96
	v_sub_u32_e32 v97, 32, v99
	v_ldexp_f32 v96, v96, v97
	v_fmamk_f32 v99, v96, 0x2e000000, v191
	v_cmp_gt_f32_e64 s[42:43], s58, v99
	v_lshl_add_u64 v[96:97], s[66:67], 0, v[106:107]
	s_cbranch_vccnz .LBB0_406
	v_lshl_add_u64 v[108:109], s[66:67], 0, v[106:107]
	s_mov_b64 s[6:7], 0

.LBB0_420:
	s_nop 1
	v_cvt_pk_bf16_f32 v80, v80, v81
	v_cvt_pk_bf16_f32 v81, v82, v83
	v_lshl_add_u64 v[82:83], v[138:139], 1, v[96:97]
	global_store_dwordx2 v[82:83], v[80:81], off offset:288
	v_or_b32_e32 v82, 48, v140
	v_mad_i64_i32 v[90:91], s[8:9], v82, s12, 0
	s_mov_b64 s[6:7], -1
	s_and_b64 vcc, exec, s[40:41]
	s_nop 1
	v_ffbh_u32_e32 v83, v247
	v_min_u32_e32 v83, 32, v83
	v_lshlrev_b64 v[80:81], v83, v[246:247]
	v_min_u32_e32 v80, 1, v80
	v_or_b32_e32 v80, v81, v80
	v_cvt_f32_u32_e32 v80, v80
	v_sub_u32_e32 v81, 32, v83
	v_ldexp_f32 v80, v80, v81
	v_fmamk_f32 v83, v80, 0x2e000000, v191
	v_cmp_gt_f32_e64 s[42:43], s58, v83
	v_lshl_add_u64 v[80:81], s[66:67], 0, v[90:91]
	s_cbranch_vccnz .LBB0_422
	v_lshl_add_u64 v[92:93], s[66:67], 0, v[90:91]
	s_mov_b64 s[6:7], 0

.LBB0_436:
	s_nop 1
	v_cvt_pk_bf16_f32 v64, v64, v65
	v_cvt_pk_bf16_f32 v65, v66, v67
	v_lshl_add_u64 v[66:67], v[138:139], 1, v[80:81]
	global_store_dwordx2 v[66:67], v[64:65], off offset:288
	v_add_u32_e32 v66, 0x80, v140
	v_mad_i64_i32 v[74:75], s[8:9], v66, s12, 0
	s_mov_b64 s[6:7], -1
	s_and_b64 vcc, exec, s[40:41]
	s_nop 1
	v_ffbh_u32_e32 v67, v249
	v_min_u32_e32 v67, 32, v67
	v_lshlrev_b64 v[64:65], v67, v[248:249]
	v_min_u32_e32 v64, 1, v64
	v_or_b32_e32 v64, v65, v64
	v_cvt_f32_u32_e32 v64, v64
	v_sub_u32_e32 v65, 32, v67
	v_ldexp_f32 v64, v64, v65
	v_fmamk_f32 v67, v64, 0x2e000000, v191
	v_cmp_gt_f32_e64 s[42:43], s58, v67
	v_lshl_add_u64 v[64:65], s[66:67], 0, v[74:75]
	s_cbranch_vccnz .LBB0_438
	v_lshl_add_u64 v[76:77], s[66:67], 0, v[74:75]
	s_mov_b64 s[6:7], 0

.LBB0_452:
	s_nop 1
	v_cvt_pk_bf16_f32 v48, v48, v49
	v_cvt_pk_bf16_f32 v49, v50, v51
	v_lshl_add_u64 v[50:51], v[138:139], 1, v[64:65]
	global_store_dwordx2 v[50:51], v[48:49], off offset:288
	v_add_u32_e32 v50, 0x90, v140
	v_mad_i64_i32 v[58:59], s[8:9], v50, s12, 0
	s_mov_b64 s[6:7], -1
	s_and_b64 vcc, exec, s[40:41]
	s_nop 1
	v_ffbh_u32_e32 v51, v251
	v_min_u32_e32 v51, 32, v51
	v_lshlrev_b64 v[48:49], v51, v[250:251]
	v_min_u32_e32 v48, 1, v48
	v_or_b32_e32 v48, v49, v48
	v_cvt_f32_u32_e32 v48, v48
	v_sub_u32_e32 v49, 32, v51
	v_ldexp_f32 v48, v48, v49
	v_fmamk_f32 v51, v48, 0x2e000000, v191
	v_cmp_gt_f32_e64 s[42:43], s58, v51
	v_lshl_add_u64 v[48:49], s[66:67], 0, v[58:59]
	s_cbranch_vccnz .LBB0_454
	v_lshl_add_u64 v[60:61], s[66:67], 0, v[58:59]
	s_mov_b64 s[6:7], 0

.LBB0_468:
	s_nop 1
	v_cvt_pk_bf16_f32 v32, v32, v33
	v_cvt_pk_bf16_f32 v33, v34, v35
	v_lshl_add_u64 v[34:35], v[138:139], 1, v[48:49]
	global_store_dwordx2 v[34:35], v[32:33], off offset:288
	v_add_u32_e32 v34, 0xa0, v140
	v_mad_i64_i32 v[42:43], s[8:9], v34, s12, 0
	s_mov_b64 s[6:7], -1
	s_and_b64 vcc, exec, s[40:41]
	s_nop 1
	v_ffbh_u32_e32 v35, v253
	v_min_u32_e32 v35, 32, v35
	v_lshlrev_b64 v[32:33], v35, v[252:253]
	v_min_u32_e32 v32, 1, v32
	v_or_b32_e32 v32, v33, v32
	v_cvt_f32_u32_e32 v32, v32
	v_sub_u32_e32 v33, 32, v35
	v_ldexp_f32 v32, v32, v33
	v_fmamk_f32 v35, v32, 0x2e000000, v191
	v_cmp_gt_f32_e64 s[42:43], s58, v35
	v_lshl_add_u64 v[32:33], s[66:67], 0, v[42:43]
	s_cbranch_vccnz .LBB0_470
	v_lshl_add_u64 v[44:45], s[66:67], 0, v[42:43]
	s_mov_b64 s[6:7], 0

.LBB0_484:
	s_nop 1
	v_cvt_pk_bf16_f32 v16, v16, v17
	v_cvt_pk_bf16_f32 v17, v18, v19
	v_lshl_add_u64 v[18:19], v[138:139], 1, v[32:33]
	global_store_dwordx2 v[18:19], v[16:17], off offset:288
	v_add_u32_e32 v18, 0xb0, v140
	v_mad_i64_i32 v[26:27], s[8:9], v18, s12, 0
	s_mov_b64 s[6:7], -1
	s_and_b64 vcc, exec, s[40:41]
	s_nop 1
	v_ffbh_u32_e32 v19, v255
	v_min_u32_e32 v19, 32, v19
	v_lshlrev_b64 v[16:17], v19, v[254:255]
	v_min_u32_e32 v16, 1, v16
	v_or_b32_e32 v16, v17, v16
	v_cvt_f32_u32_e32 v16, v16
	v_sub_u32_e32 v17, 32, v19
	v_ldexp_f32 v16, v16, v17
	v_fmamk_f32 v19, v16, 0x2e000000, v191
	v_cmp_gt_f32_e64 s[42:43], s58, v19
	v_lshl_add_u64 v[16:17], s[66:67], 0, v[26:27]
	s_cbranch_vccnz .LBB0_486
	v_lshl_add_u64 v[28:29], s[66:67], 0, v[26:27]
	s_mov_b64 s[6:7], 0

.LBB0_841:
	s_lshl_b32 s8, s39, 8
	s_add_i32 s8, s8, s20
	v_or_b32_e32 v142, s8, v148
	v_readlane_b32 s10, v236, 16
	v_ashrrev_i32_e32 v143, 31, v142
	v_readlane_b32 s11, v236, 17
	v_lshl_or_b32 v140, s38, 8, v150
	v_ashrrev_i32_e32 v141, 31, v140
	v_lshl_add_u64 v[144:145], v[142:143], 3, s[10:11]
	global_load_dwordx2 v[146:147], v[144:145], off
	global_load_dwordx2 v[242:243], v[144:145], off offset:128
	global_load_dwordx2 v[244:245], v[144:145], off offset:256
	global_load_dwordx2 v[246:247], v[144:145], off offset:384
	global_load_dwordx2 v[248:249], v[144:145], off offset:1024
	global_load_dwordx2 v[250:251], v[144:145], off offset:1152
	global_load_dwordx2 v[252:253], v[144:145], off offset:1280
	global_load_dwordx2 v[254:255], v[144:145], off offset:1408
	s_ashr_i32 s8, s8, 11
	s_mul_i32 s8, s8, 15
	s_movk_i32 s9, 0x7ff
	s_addk_i32 s8, 0xf80f
	s_waitcnt vmcnt(0)
	v_ffbh_u32_e32 v152, v147
	v_min_u32_e32 v152, 32, v152
	v_lshlrev_b64 v[146:147], v152, v[146:147]
	v_min_u32_e32 v146, 1, v146
	v_or_b32_e32 v146, v147, v146
	v_cvt_f32_u32_e32 v146, v146
	v_sub_u32_e32 v147, 32, v152
	v_ldexp_f32 v146, v146, v147
	v_fmamk_f32 v146, v146, 0x2e000000, v191
	v_cmp_gt_f32_e32 vcc, s58, v146
	v_mul_f32_e32 v147, 0x4b800000, v146
	s_nop 0
	v_cndmask_b32_e32 v146, v146, v147, vcc
	v_rsq_f32_e32 v146, v146
	s_nop 0
	v_mul_f32_e32 v147, 0x45800000, v146
	v_cndmask_b32_e32 v152, v146, v147, vcc
	v_lshlrev_b64 v[146:147], 12, v[142:143]
	v_lshl_add_u64 v[154:155], s[66:67], 0, v[146:147]
	v_lshlrev_b64 v[146:147], 1, v[140:141]
	v_pk_mul_f32 v[126:127], v[126:127], v[152:153] op_sel_hi:[1,0]
	v_pk_mul_f32 v[124:125], v[124:125], v[152:153] op_sel_hi:[1,0]
	v_pk_mul_f32 v[156:157], v[122:123], v[152:153] op_sel_hi:[1,0]
	v_pk_mul_f32 v[122:123], v[120:121], v[152:153] op_sel_hi:[1,0]
	v_lshl_add_u64 v[154:155], v[154:155], 0, v[146:147]
	v_cvt_pk_bf16_f32 v120, v124, v125
	v_cvt_pk_bf16_f32 v121, v126, v127
	v_cvt_pk_bf16_f32 v122, v122, v123
	v_cvt_pk_bf16_f32 v123, v156, v157
	global_store_dwordx4 v[154:155], v[120:123], off
	v_pk_mul_f32 v[118:119], v[118:119], v[152:153] op_sel_hi:[1,0]
	v_pk_mul_f32 v[116:117], v[116:117], v[152:153] op_sel_hi:[1,0]
	v_pk_mul_f32 v[120:121], v[114:115], v[152:153] op_sel_hi:[1,0]
	v_pk_mul_f32 v[114:115], v[112:113], v[152:153] op_sel_hi:[1,0]
	v_cvt_pk_bf16_f32 v112, v116, v117
	v_cvt_pk_bf16_f32 v113, v118, v119
	v_cvt_pk_bf16_f32 v114, v114, v115
	v_cvt_pk_bf16_f32 v115, v120, v121
	global_store_dwordx4 v[154:155], v[112:115], off offset:256
	s_nop 1
	v_ffbh_u32_e32 v116, v243
	v_min_u32_e32 v116, 32, v116
	v_lshlrev_b64 v[114:115], v116, v[242:243]
	v_min_u32_e32 v114, 1, v114
	v_or_b32_e32 v114, v115, v114
	v_cvt_f32_u32_e32 v114, v114
	v_sub_u32_e32 v115, 32, v116
	v_or_b32_e32 v112, 16, v142
	v_ashrrev_i32_e32 v113, 31, v112
	v_ldexp_f32 v114, v114, v115
	v_fmamk_f32 v114, v114, 0x2e000000, v191
	v_cmp_gt_f32_e32 vcc, s58, v114
	v_mul_f32_e32 v115, 0x4b800000, v114
	v_lshlrev_b64 v[112:113], 12, v[112:113]
	v_cndmask_b32_e32 v114, v114, v115, vcc
	v_rsq_f32_e32 v114, v114
	v_lshl_add_u64 v[112:113], s[66:67], 0, v[112:113]
	v_lshl_add_u64 v[112:113], v[112:113], 0, v[146:147]
	v_mul_f32_e32 v115, 0x45800000, v114
	v_cndmask_b32_e32 v114, v114, v115, vcc
	v_pk_mul_f32 v[110:111], v[110:111], v[114:115] op_sel_hi:[1,0]
	v_pk_mul_f32 v[108:109], v[108:109], v[114:115] op_sel_hi:[1,0]
	v_pk_mul_f32 v[116:117], v[106:107], v[114:115] op_sel_hi:[1,0]
	v_pk_mul_f32 v[106:107], v[104:105], v[114:115] op_sel_hi:[1,0]
	v_cvt_pk_bf16_f32 v104, v108, v109
	v_cvt_pk_bf16_f32 v105, v110, v111
	v_cvt_pk_bf16_f32 v106, v106, v107
	v_cvt_pk_bf16_f32 v107, v116, v117
	global_store_dwordx4 v[112:113], v[104:107], off
	v_pk_mul_f32 v[102:103], v[102:103], v[114:115] op_sel_hi:[1,0]
	v_pk_mul_f32 v[100:101], v[100:101], v[114:115] op_sel_hi:[1,0]
	v_pk_mul_f32 v[104:105], v[98:99], v[114:115] op_sel_hi:[1,0]
	v_pk_mul_f32 v[98:99], v[96:97], v[114:115] op_sel_hi:[1,0]
	v_cvt_pk_bf16_f32 v96, v100, v101
	v_cvt_pk_bf16_f32 v97, v102, v103
	v_cvt_pk_bf16_f32 v98, v98, v99
	v_cvt_pk_bf16_f32 v99, v104, v105
	global_store_dwordx4 v[112:113], v[96:99], off offset:256
	s_nop 1
	v_ffbh_u32_e32 v100, v245
	v_min_u32_e32 v100, 32, v100
	v_lshlrev_b64 v[98:99], v100, v[244:245]
	v_min_u32_e32 v98, 1, v98
	v_or_b32_e32 v98, v99, v98
	v_cvt_f32_u32_e32 v98, v98
	v_sub_u32_e32 v99, 32, v100
	v_or_b32_e32 v96, 32, v142
	v_ashrrev_i32_e32 v97, 31, v96
	v_ldexp_f32 v98, v98, v99
	v_fmamk_f32 v98, v98, 0x2e000000, v191
	v_cmp_gt_f32_e32 vcc, s58, v98
	v_mul_f32_e32 v99, 0x4b800000, v98
	v_lshlrev_b64 v[96:97], 12, v[96:97]
	v_cndmask_b32_e32 v98, v98, v99, vcc
	v_rsq_f32_e32 v98, v98
	v_lshl_add_u64 v[96:97], s[66:67], 0, v[96:97]
	v_lshl_add_u64 v[96:97], v[96:97], 0, v[146:147]
	v_mul_f32_e32 v99, 0x45800000, v98
	v_cndmask_b32_e32 v98, v98, v99, vcc
	v_pk_mul_f32 v[94:95], v[94:95], v[98:99] op_sel_hi:[1,0]
	v_pk_mul_f32 v[92:93], v[92:93], v[98:99] op_sel_hi:[1,0]
	v_pk_mul_f32 v[100:101], v[90:91], v[98:99] op_sel_hi:[1,0]
	v_pk_mul_f32 v[90:91], v[88:89], v[98:99] op_sel_hi:[1,0]
	v_cvt_pk_bf16_f32 v88, v92, v93
	v_cvt_pk_bf16_f32 v89, v94, v95
	v_cvt_pk_bf16_f32 v90, v90, v91
	v_cvt_pk_bf16_f32 v91, v100, v101
	global_store_dwordx4 v[96:97], v[88:91], off
	v_pk_mul_f32 v[86:87], v[86:87], v[98:99] op_sel_hi:[1,0]
	v_pk_mul_f32 v[84:85], v[84:85], v[98:99] op_sel_hi:[1,0]
	v_pk_mul_f32 v[88:89], v[82:83], v[98:99] op_sel_hi:[1,0]
	v_pk_mul_f32 v[82:83], v[80:81], v[98:99] op_sel_hi:[1,0]
	v_cvt_pk_bf16_f32 v80, v84, v85
	v_cvt_pk_bf16_f32 v81, v86, v87
	v_cvt_pk_bf16_f32 v82, v82, v83
	v_cvt_pk_bf16_f32 v83, v88, v89
	global_store_dwordx4 v[96:97], v[80:83], off offset:256
	s_nop 1
	v_ffbh_u32_e32 v84, v247
	v_min_u32_e32 v84, 32, v84
	v_lshlrev_b64 v[80:81], v84, v[246:247]
	v_min_u32_e32 v80, 1, v80
	v_or_b32_e32 v80, v81, v80
	v_cvt_f32_u32_e32 v80, v80
	v_sub_u32_e32 v81, 32, v84
	v_or_b32_e32 v82, 48, v142
	v_ashrrev_i32_e32 v83, 31, v82
	v_ldexp_f32 v80, v80, v81
	v_fmamk_f32 v80, v80, 0x2e000000, v191
	v_cmp_gt_f32_e32 vcc, s58, v80
	v_mul_f32_e32 v81, 0x4b800000, v80
	v_lshlrev_b64 v[82:83], 12, v[82:83]
	v_cndmask_b32_e32 v80, v80, v81, vcc
	v_rsq_f32_e32 v80, v80
	v_lshl_add_u64 v[82:83], s[66:67], 0, v[82:83]
	v_lshl_add_u64 v[84:85], v[82:83], 0, v[146:147]
	v_mul_f32_e32 v81, 0x45800000, v80
	v_cndmask_b32_e32 v80, v80, v81, vcc
	v_bitop3_b32 v81, v142, s9, 48 bitop3:0xc8
	v_add_u32_e32 v82, s8, v81
	v_ashrrev_i32_e32 v83, 31, v82
	v_lshlrev_b64 v[82:83], 13, v[82:83]
	v_lshl_add_u64 v[82:83], s[6:7], 0, v[82:83]
	s_movk_i32 s8, 0x7f0
	v_pk_mul_f32 v[78:79], v[78:79], v[80:81] op_sel_hi:[1,0]
	v_pk_mul_f32 v[76:77], v[76:77], v[80:81] op_sel_hi:[1,0]
	v_pk_mul_f32 v[74:75], v[74:75], v[80:81] op_sel_hi:[1,0]
	v_pk_mul_f32 v[72:73], v[72:73], v[80:81] op_sel_hi:[1,0]
	v_lshl_add_u64 v[82:83], v[140:141], 2, v[82:83]
	v_cmp_lt_u32_e32 vcc, s8, v81
	v_cvt_pk_bf16_f32 v86, v76, v77
	v_cvt_pk_bf16_f32 v87, v78, v79
	v_cvt_pk_bf16_f32 v88, v72, v73
	v_cvt_pk_bf16_f32 v89, v74, v75
	global_store_dwordx4 v[84:85], v[86:89], off
	s_and_saveexec_b64 s[8:9], vcc
	s_cbranch_execz .LBB0_843
	global_store_dwordx4 v[82:83], v[76:79], off
	global_store_dwordx4 v[82:83], v[72:75], off offset:16

.LBB0_845:
	s_or_b64 exec, exec, s[8:9]
	v_add_u32_e32 v66, 0x80, v142
	v_ashrrev_i32_e32 v67, 31, v66
	v_ashrrev_i32_e32 v64, 11, v66
	v_lshlrev_b64 v[66:67], 12, v[66:67]
	v_lshl_add_u64 v[66:67], s[66:67], 0, v[66:67]
	v_lshl_add_u64 v[66:67], v[66:67], 0, v[146:147]
	s_mov_b64 s[8:9], 0x90000
	v_mul_i32_i24_e32 v64, 15, v64
	s_nop 1
	v_ffbh_u32_e32 v65, v249
	v_min_u32_e32 v65, 32, v65
	v_lshlrev_b64 v[68:69], v65, v[248:249]
	v_min_u32_e32 v68, 1, v68
	v_or_b32_e32 v68, v69, v68
	v_cvt_f32_u32_e32 v68, v68
	v_sub_u32_e32 v65, 32, v65
	v_ldexp_f32 v65, v68, v65
	v_fmamk_f32 v65, v65, 0x2e000000, v191
	v_cmp_gt_f32_e32 vcc, s58, v65
	v_mul_f32_e32 v68, 0x4b800000, v65
	s_nop 0
	v_cndmask_b32_e32 v65, v65, v68, vcc
	v_rsq_f32_e32 v65, v65
	s_nop 0
	v_mul_f32_e32 v68, 0x45800000, v65
	v_cndmask_b32_e32 v68, v65, v68, vcc
	v_pk_mul_f32 v[62:63], v[62:63], v[68:69] op_sel_hi:[1,0]
	v_pk_mul_f32 v[60:61], v[60:61], v[68:69] op_sel_hi:[1,0]
	v_pk_mul_f32 v[70:71], v[58:59], v[68:69] op_sel_hi:[1,0]
	v_pk_mul_f32 v[58:59], v[56:57], v[68:69] op_sel_hi:[1,0]
	v_cvt_pk_bf16_f32 v56, v60, v61
	v_cvt_pk_bf16_f32 v57, v62, v63
	v_cvt_pk_bf16_f32 v58, v58, v59
	v_cvt_pk_bf16_f32 v59, v70, v71
	global_store_dwordx4 v[66:67], v[56:59], off
	v_pk_mul_f32 v[54:55], v[54:55], v[68:69] op_sel_hi:[1,0]
	v_pk_mul_f32 v[52:53], v[52:53], v[68:69] op_sel_hi:[1,0]
	v_pk_mul_f32 v[56:57], v[50:51], v[68:69] op_sel_hi:[1,0]
	v_pk_mul_f32 v[50:51], v[48:49], v[68:69] op_sel_hi:[1,0]
	v_cvt_pk_bf16_f32 v48, v52, v53
	v_cvt_pk_bf16_f32 v49, v54, v55
	v_cvt_pk_bf16_f32 v50, v50, v51
	v_cvt_pk_bf16_f32 v51, v56, v57
	global_store_dwordx4 v[66:67], v[48:51], off offset:256
	s_nop 1
	v_ffbh_u32_e32 v50, v251
	v_min_u32_e32 v50, 32, v50
	v_lshlrev_b64 v[48:49], v50, v[250:251]
	v_min_u32_e32 v48, 1, v48
	v_or_b32_e32 v48, v49, v48
	v_cvt_f32_u32_e32 v48, v48
	v_sub_u32_e32 v49, 32, v50
	v_ldexp_f32 v48, v48, v49
	v_fmamk_f32 v48, v48, 0x2e000000, v191
	v_cmp_gt_f32_e32 vcc, s58, v48
	v_mul_f32_e32 v49, 0x4b800000, v48
	s_nop 0
	v_cndmask_b32_e32 v48, v48, v49, vcc
	v_rsq_f32_e32 v48, v48
	s_nop 0
	v_mul_f32_e32 v49, 0x45800000, v48
	v_cndmask_b32_e32 v50, v48, v49, vcc
	v_lshlrev_b64 v[48:49], 12, v[142:143]
	v_lshl_add_u64 v[48:49], s[66:67], 0, v[48:49]
	v_lshl_add_u64 v[48:49], v[48:49], 0, v[146:147]
	v_lshl_add_u64 v[52:53], v[48:49], 0, s[8:9]
	v_pk_mul_f32 v[44:45], v[44:45], v[50:51] op_sel_hi:[1,0]
	s_mov_b32 s8, 0x90000
	v_pk_mul_f32 v[46:47], v[46:47], v[50:51] op_sel_hi:[1,0]
	v_pk_mul_f32 v[54:55], v[42:43], v[50:51] op_sel_hi:[1,0]
	v_pk_mul_f32 v[42:43], v[40:41], v[50:51] op_sel_hi:[1,0]
	v_cvt_pk_bf16_f32 v40, v44, v45
	v_add_co_u32_e32 v44, vcc, s8, v48
	v_cvt_pk_bf16_f32 v41, v46, v47
	v_cvt_pk_bf16_f32 v42, v42, v43
	v_cvt_pk_bf16_f32 v43, v54, v55
	v_addc_co_u32_e32 v45, vcc, 0, v49, vcc
	global_store_dwordx4 v[44:45], v[40:43], off
	v_pk_mul_f32 v[38:39], v[38:39], v[50:51] op_sel_hi:[1,0]
	v_pk_mul_f32 v[36:37], v[36:37], v[50:51] op_sel_hi:[1,0]
	v_pk_mul_f32 v[40:41], v[34:35], v[50:51] op_sel_hi:[1,0]
	v_pk_mul_f32 v[34:35], v[32:33], v[50:51] op_sel_hi:[1,0]
	v_cvt_pk_bf16_f32 v32, v36, v37
	v_cvt_pk_bf16_f32 v33, v38, v39
	v_cvt_pk_bf16_f32 v34, v34, v35
	v_cvt_pk_bf16_f32 v35, v40, v41
	global_store_dwordx4 v[52:53], v[32:35], off offset:256
	s_mov_b64 s[8:9], 0xa0000
	s_nop 1
	v_ffbh_u32_e32 v34, v253
	v_min_u32_e32 v34, 32, v34
	v_lshlrev_b64 v[32:33], v34, v[252:253]
	v_min_u32_e32 v32, 1, v32
	v_or_b32_e32 v32, v33, v32
	v_cvt_f32_u32_e32 v32, v32
	v_sub_u32_e32 v33, 32, v34
	v_lshl_add_u64 v[34:35], v[48:49], 0, s[8:9]
	s_mov_b32 s8, 0xa0000
	v_ldexp_f32 v32, v32, v33
	v_fmamk_f32 v32, v32, 0x2e000000, v191
	v_cmp_gt_f32_e32 vcc, s58, v32
	v_mul_f32_e32 v33, 0x4b800000, v32
	s_nop 0
	v_cndmask_b32_e32 v32, v32, v33, vcc
	v_rsq_f32_e32 v32, v32
	s_nop 0
	v_mul_f32_e32 v33, 0x45800000, v32
	v_cndmask_b32_e32 v32, v32, v33, vcc
	v_pk_mul_f32 v[28:29], v[28:29], v[32:33] op_sel_hi:[1,0]
	v_pk_mul_f32 v[30:31], v[30:31], v[32:33] op_sel_hi:[1,0]
	v_pk_mul_f32 v[36:37], v[26:27], v[32:33] op_sel_hi:[1,0]
	v_pk_mul_f32 v[26:27], v[24:25], v[32:33] op_sel_hi:[1,0]
	v_cvt_pk_bf16_f32 v24, v28, v29
	v_add_co_u32_e32 v28, vcc, s8, v48
	v_cvt_pk_bf16_f32 v25, v30, v31
	v_cvt_pk_bf16_f32 v26, v26, v27
	v_cvt_pk_bf16_f32 v27, v36, v37
	v_addc_co_u32_e32 v29, vcc, 0, v49, vcc
	global_store_dwordx4 v[28:29], v[24:27], off
	v_pk_mul_f32 v[22:23], v[22:23], v[32:33] op_sel_hi:[1,0]
	v_pk_mul_f32 v[20:21], v[20:21], v[32:33] op_sel_hi:[1,0]
	v_pk_mul_f32 v[24:25], v[18:19], v[32:33] op_sel_hi:[1,0]
	v_pk_mul_f32 v[18:19], v[16:17], v[32:33] op_sel_hi:[1,0]
	v_cvt_pk_bf16_f32 v16, v20, v21
	v_cvt_pk_bf16_f32 v17, v22, v23
	v_cvt_pk_bf16_f32 v18, v18, v19
	v_cvt_pk_bf16_f32 v19, v24, v25
	global_store_dwordx4 v[34:35], v[16:19], off offset:256
	s_movk_i32 s8, 0xf80f
	v_add_u32_e32 v16, 0xb0, v142
	v_ashrrev_i32_e32 v17, 31, v16
	s_nop 1
	v_ffbh_u32_e32 v20, v255
	v_min_u32_e32 v20, 32, v20
	v_lshlrev_b64 v[18:19], v20, v[254:255]
	v_min_u32_e32 v18, 1, v18
	v_or_b32_e32 v18, v19, v18
	v_cvt_f32_u32_e32 v18, v18
	v_sub_u32_e32 v19, 32, v20
	v_ldexp_f32 v18, v18, v19
	v_fmamk_f32 v18, v18, 0x2e000000, v191
	v_cmp_gt_f32_e32 vcc, s58, v18
	v_mul_f32_e32 v19, 0x4b800000, v18
	s_nop 0
	v_cndmask_b32_e32 v18, v18, v19, vcc
	v_rsq_f32_e32 v18, v18
	s_nop 0
	v_mul_f32_e32 v19, 0x45800000, v18
	v_cndmask_b32_e32 v18, v18, v19, vcc
	v_and_b32_e32 v19, 0x7ff, v16
	v_add3_u32 v20, v19, v64, s8
	v_ashrrev_i32_e32 v21, 31, v20
	v_lshlrev_b64 v[16:17], 12, v[16:17]
	v_lshlrev_b64 v[20:21], 13, v[20:21]
	v_lshl_add_u64 v[16:17], s[66:67], 0, v[16:17]
	v_lshl_add_u64 v[20:21], s[6:7], 0, v[20:21]
	s_movk_i32 s8, 0x7f0
	v_pk_mul_f32 v[14:15], v[14:15], v[18:19] op_sel_hi:[1,0]
	v_pk_mul_f32 v[12:13], v[12:13], v[18:19] op_sel_hi:[1,0]
	v_pk_mul_f32 v[10:11], v[10:11], v[18:19] op_sel_hi:[1,0]
	v_pk_mul_f32 v[8:9], v[8:9], v[18:19] op_sel_hi:[1,0]
	v_lshl_add_u64 v[16:17], v[16:17], 0, v[146:147]
	v_lshl_add_u64 v[20:21], v[140:141], 2, v[20:21]
	v_cmp_lt_u32_e32 vcc, s8, v19
	v_cvt_pk_bf16_f32 v22, v12, v13
	v_cvt_pk_bf16_f32 v23, v14, v15
	v_cvt_pk_bf16_f32 v24, v8, v9
	v_cvt_pk_bf16_f32 v25, v10, v11
	global_store_dwordx4 v[16:17], v[22:25], off
	s_and_saveexec_b64 s[8:9], vcc
	s_cbranch_execz .LBB0_847
	global_store_dwordx4 v[20:21], v[12:15], off
	global_store_dwordx4 v[20:21], v[8:11], off offset:16

.LBB0_1151:
	v_lshl_add_u32 v146, s18, 8, v148
	v_ashrrev_i32_e32 v147, 31, v146
	v_lshl_add_u64 v[142:143], v[146:147], 3, s[40:41]
	global_load_dwordx2 v[144:145], v[142:143], off
	global_load_dwordx2 v[242:243], v[142:143], off offset:128
	global_load_dwordx2 v[244:245], v[142:143], off offset:256
	global_load_dwordx2 v[246:247], v[142:143], off offset:384
	global_load_dwordx2 v[248:249], v[142:143], off offset:1024
	global_load_dwordx2 v[250:251], v[142:143], off offset:1152
	global_load_dwordx2 v[252:253], v[142:143], off offset:1280
	global_load_dwordx2 v[254:255], v[142:143], off offset:1408
	v_lshl_or_b32 v140, s14, 8, v150
	v_readlane_b32 s6, v240, 62
	v_ashrrev_i32_e32 v141, 31, v140
	v_readlane_b32 s7, v240, 63
	v_readlane_b32 s8, v237, 51
	v_readlane_b32 s11, v237, 54
	s_mov_b64 s[28:29], s[34:35]
	v_readlane_b32 s9, v237, 52
	v_readlane_b32 s10, v237, 53
	s_waitcnt vmcnt(0)
	v_ffbh_u32_e32 v152, v145
	v_min_u32_e32 v152, 32, v152
	v_lshlrev_b64 v[144:145], v152, v[144:145]
	v_min_u32_e32 v144, 1, v144
	v_or_b32_e32 v144, v145, v144
	v_cvt_f32_u32_e32 v144, v144
	v_sub_u32_e32 v145, 32, v152
	v_ldexp_f32 v144, v144, v145
	v_fmamk_f32 v144, v144, 0x2e000000, v191
	v_cmp_gt_f32_e32 vcc, s58, v144
	v_mul_f32_e32 v145, 0x4b800000, v144
	s_nop 0
	v_cndmask_b32_e32 v144, v144, v145, vcc
	v_rsq_f32_e32 v144, v144
	s_nop 0
	v_mul_f32_e32 v145, 0x45800000, v144
	v_cndmask_b32_e32 v152, v144, v145, vcc
	v_lshlrev_b64 v[144:145], 10, v[146:147]
	v_lshl_add_u64 v[154:155], s[6:7], 0, v[144:145]
	v_lshlrev_b64 v[144:145], 1, v[140:141]
	v_lshl_add_u64 v[140:141], v[154:155], 0, v[144:145]
	v_pk_mul_f32 v[126:127], v[126:127], v[152:153] op_sel_hi:[1,0]
	v_pk_mul_f32 v[124:125], v[124:125], v[152:153] op_sel_hi:[1,0]
	v_pk_mul_f32 v[154:155], v[122:123], v[152:153] op_sel_hi:[1,0]
	v_pk_mul_f32 v[122:123], v[120:121], v[152:153] op_sel_hi:[1,0]
	v_cvt_pk_bf16_f32 v120, v124, v125
	v_cvt_pk_bf16_f32 v121, v126, v127
	v_cvt_pk_bf16_f32 v122, v122, v123
	v_cvt_pk_bf16_f32 v123, v154, v155
	global_store_dwordx4 v[140:141], v[120:123], off
	v_pk_mul_f32 v[118:119], v[118:119], v[152:153] op_sel_hi:[1,0]
	v_pk_mul_f32 v[116:117], v[116:117], v[152:153] op_sel_hi:[1,0]
	v_pk_mul_f32 v[120:121], v[114:115], v[152:153] op_sel_hi:[1,0]
	v_pk_mul_f32 v[114:115], v[112:113], v[152:153] op_sel_hi:[1,0]
	v_cvt_pk_bf16_f32 v112, v116, v117
	v_cvt_pk_bf16_f32 v113, v118, v119
	v_cvt_pk_bf16_f32 v114, v114, v115
	v_cvt_pk_bf16_f32 v115, v120, v121
	global_store_dwordx4 v[140:141], v[112:115], off offset:256
	s_nop 1
	v_or_b32_e32 v112, 16, v146
	v_ashrrev_i32_e32 v113, 31, v112
	v_lshl_add_u64 v[114:115], v[112:113], 3, s[40:41]
	v_lshlrev_b64 v[112:113], 10, v[112:113]
	v_lshl_add_u64 v[112:113], s[6:7], 0, v[112:113]
	v_lshl_add_u64 v[112:113], v[112:113], 0, v[144:145]
	s_nop 1
	v_ffbh_u32_e32 v116, v243
	v_min_u32_e32 v116, 32, v116
	v_lshlrev_b64 v[114:115], v116, v[242:243]
	v_min_u32_e32 v114, 1, v114
	v_or_b32_e32 v114, v115, v114
	v_cvt_f32_u32_e32 v114, v114
	v_sub_u32_e32 v115, 32, v116
	v_ldexp_f32 v114, v114, v115
	v_fmamk_f32 v114, v114, 0x2e000000, v191
	v_cmp_gt_f32_e32 vcc, s58, v114
	v_mul_f32_e32 v115, 0x4b800000, v114
	s_nop 0
	v_cndmask_b32_e32 v114, v114, v115, vcc
	v_rsq_f32_e32 v114, v114
	s_nop 0
	v_mul_f32_e32 v115, 0x45800000, v114
	v_cndmask_b32_e32 v114, v114, v115, vcc
	v_pk_mul_f32 v[110:111], v[110:111], v[114:115] op_sel_hi:[1,0]
	v_pk_mul_f32 v[108:109], v[108:109], v[114:115] op_sel_hi:[1,0]
	v_pk_mul_f32 v[116:117], v[106:107], v[114:115] op_sel_hi:[1,0]
	v_pk_mul_f32 v[106:107], v[104:105], v[114:115] op_sel_hi:[1,0]
	v_cvt_pk_bf16_f32 v104, v108, v109
	v_cvt_pk_bf16_f32 v105, v110, v111
	v_cvt_pk_bf16_f32 v106, v106, v107
	v_cvt_pk_bf16_f32 v107, v116, v117
	global_store_dwordx4 v[112:113], v[104:107], off
	v_pk_mul_f32 v[102:103], v[102:103], v[114:115] op_sel_hi:[1,0]
	v_pk_mul_f32 v[100:101], v[100:101], v[114:115] op_sel_hi:[1,0]
	v_pk_mul_f32 v[104:105], v[98:99], v[114:115] op_sel_hi:[1,0]
	v_pk_mul_f32 v[98:99], v[96:97], v[114:115] op_sel_hi:[1,0]
	v_cvt_pk_bf16_f32 v96, v100, v101
	v_cvt_pk_bf16_f32 v97, v102, v103
	v_cvt_pk_bf16_f32 v98, v98, v99
	v_cvt_pk_bf16_f32 v99, v104, v105
	global_store_dwordx4 v[112:113], v[96:99], off offset:256
	s_nop 1
	v_or_b32_e32 v96, 32, v146
	v_ashrrev_i32_e32 v97, 31, v96
	v_lshl_add_u64 v[98:99], v[96:97], 3, s[40:41]
	v_lshlrev_b64 v[96:97], 10, v[96:97]
	v_lshl_add_u64 v[96:97], s[6:7], 0, v[96:97]
	v_lshl_add_u64 v[96:97], v[96:97], 0, v[144:145]
	s_nop 1
	v_ffbh_u32_e32 v100, v245
	v_min_u32_e32 v100, 32, v100
	v_lshlrev_b64 v[98:99], v100, v[244:245]
	v_min_u32_e32 v98, 1, v98
	v_or_b32_e32 v98, v99, v98
	v_cvt_f32_u32_e32 v98, v98
	v_sub_u32_e32 v99, 32, v100
	v_ldexp_f32 v98, v98, v99
	v_fmamk_f32 v98, v98, 0x2e000000, v191
	v_cmp_gt_f32_e32 vcc, s58, v98
	v_mul_f32_e32 v99, 0x4b800000, v98
	s_nop 0
	v_cndmask_b32_e32 v98, v98, v99, vcc
	v_rsq_f32_e32 v98, v98
	s_nop 0
	v_mul_f32_e32 v99, 0x45800000, v98
	v_cndmask_b32_e32 v98, v98, v99, vcc
	v_pk_mul_f32 v[94:95], v[94:95], v[98:99] op_sel_hi:[1,0]
	v_pk_mul_f32 v[92:93], v[92:93], v[98:99] op_sel_hi:[1,0]
	v_pk_mul_f32 v[100:101], v[90:91], v[98:99] op_sel_hi:[1,0]
	v_pk_mul_f32 v[90:91], v[88:89], v[98:99] op_sel_hi:[1,0]
	v_cvt_pk_bf16_f32 v88, v92, v93
	v_cvt_pk_bf16_f32 v89, v94, v95
	v_cvt_pk_bf16_f32 v90, v90, v91
	v_cvt_pk_bf16_f32 v91, v100, v101
	global_store_dwordx4 v[96:97], v[88:91], off
	v_pk_mul_f32 v[86:87], v[86:87], v[98:99] op_sel_hi:[1,0]
	v_pk_mul_f32 v[84:85], v[84:85], v[98:99] op_sel_hi:[1,0]
	v_pk_mul_f32 v[88:89], v[82:83], v[98:99] op_sel_hi:[1,0]
	v_pk_mul_f32 v[82:83], v[80:81], v[98:99] op_sel_hi:[1,0]
	v_cvt_pk_bf16_f32 v80, v84, v85
	v_cvt_pk_bf16_f32 v81, v86, v87
	v_cvt_pk_bf16_f32 v82, v82, v83
	v_cvt_pk_bf16_f32 v83, v88, v89
	global_store_dwordx4 v[96:97], v[80:83], off offset:256
	s_nop 1
	v_or_b32_e32 v80, 48, v146
	v_ashrrev_i32_e32 v81, 31, v80
	v_lshl_add_u64 v[82:83], v[80:81], 3, s[40:41]
	v_lshlrev_b64 v[80:81], 10, v[80:81]
	v_lshl_add_u64 v[80:81], s[6:7], 0, v[80:81]
	v_lshl_add_u64 v[80:81], v[80:81], 0, v[144:145]
	s_mov_b64 s[6:7], 0x20000
	s_nop 1
	v_ffbh_u32_e32 v84, v247
	v_min_u32_e32 v84, 32, v84
	v_lshlrev_b64 v[82:83], v84, v[246:247]
	v_min_u32_e32 v82, 1, v82
	v_or_b32_e32 v82, v83, v82
	v_cvt_f32_u32_e32 v82, v82
	v_sub_u32_e32 v83, 32, v84
	v_ldexp_f32 v82, v82, v83
	v_fmamk_f32 v82, v82, 0x2e000000, v191
	v_cmp_gt_f32_e32 vcc, s58, v82
	v_mul_f32_e32 v83, 0x4b800000, v82
	s_nop 0
	v_cndmask_b32_e32 v82, v82, v83, vcc
	v_rsq_f32_e32 v82, v82
	s_nop 0
	v_mul_f32_e32 v83, 0x45800000, v82
	v_cndmask_b32_e32 v82, v82, v83, vcc
	v_pk_mul_f32 v[78:79], v[78:79], v[82:83] op_sel_hi:[1,0]
	v_pk_mul_f32 v[76:77], v[76:77], v[82:83] op_sel_hi:[1,0]
	v_pk_mul_f32 v[84:85], v[74:75], v[82:83] op_sel_hi:[1,0]
	v_pk_mul_f32 v[74:75], v[72:73], v[82:83] op_sel_hi:[1,0]
	v_cvt_pk_bf16_f32 v72, v76, v77
	v_cvt_pk_bf16_f32 v73, v78, v79
	v_cvt_pk_bf16_f32 v74, v74, v75
	v_cvt_pk_bf16_f32 v75, v84, v85
	global_store_dwordx4 v[80:81], v[72:75], off
	v_pk_mul_f32 v[70:71], v[70:71], v[82:83] op_sel_hi:[1,0]
	v_pk_mul_f32 v[68:69], v[68:69], v[82:83] op_sel_hi:[1,0]
	v_pk_mul_f32 v[72:73], v[66:67], v[82:83] op_sel_hi:[1,0]
	v_pk_mul_f32 v[66:67], v[64:65], v[82:83] op_sel_hi:[1,0]
	v_cvt_pk_bf16_f32 v64, v68, v69
	v_cvt_pk_bf16_f32 v65, v70, v71
	v_cvt_pk_bf16_f32 v66, v66, v67
	v_cvt_pk_bf16_f32 v67, v72, v73
	global_store_dwordx4 v[80:81], v[64:67], off offset:256
	s_nop 1
	v_ffbh_u32_e32 v66, v249
	v_min_u32_e32 v66, 32, v66
	v_lshlrev_b64 v[64:65], v66, v[248:249]
	v_min_u32_e32 v64, 1, v64
	v_or_b32_e32 v64, v65, v64
	v_cvt_f32_u32_e32 v64, v64
	v_sub_u32_e32 v65, 32, v66
	v_lshl_add_u64 v[66:67], v[140:141], 0, s[6:7]
	s_mov_b64 s[6:7], 0x24000
	v_ldexp_f32 v64, v64, v65
	v_fmamk_f32 v64, v64, 0x2e000000, v191
	v_cmp_gt_f32_e32 vcc, s58, v64
	v_mul_f32_e32 v65, 0x4b800000, v64
	s_nop 0
	v_cndmask_b32_e32 v64, v64, v65, vcc
	v_rsq_f32_e32 v64, v64
	s_nop 0
	v_mul_f32_e32 v65, 0x45800000, v64
	v_cndmask_b32_e32 v64, v64, v65, vcc
	v_pk_mul_f32 v[60:61], v[60:61], v[64:65] op_sel_hi:[1,0]
	v_pk_mul_f32 v[62:63], v[62:63], v[64:65] op_sel_hi:[1,0]
	v_pk_mul_f32 v[68:69], v[58:59], v[64:65] op_sel_hi:[1,0]
	v_pk_mul_f32 v[58:59], v[56:57], v[64:65] op_sel_hi:[1,0]
	v_cvt_pk_bf16_f32 v56, v60, v61
	v_add_co_u32_e32 v60, vcc, s11, v140
	v_cvt_pk_bf16_f32 v57, v62, v63
	v_cvt_pk_bf16_f32 v58, v58, v59
	v_cvt_pk_bf16_f32 v59, v68, v69
	v_addc_co_u32_e32 v61, vcc, 0, v141, vcc
	global_store_dwordx4 v[60:61], v[56:59], off
	v_pk_mul_f32 v[54:55], v[54:55], v[64:65] op_sel_hi:[1,0]
	v_pk_mul_f32 v[52:53], v[52:53], v[64:65] op_sel_hi:[1,0]
	v_pk_mul_f32 v[56:57], v[50:51], v[64:65] op_sel_hi:[1,0]
	v_pk_mul_f32 v[50:51], v[48:49], v[64:65] op_sel_hi:[1,0]
	v_cvt_pk_bf16_f32 v48, v52, v53
	v_cvt_pk_bf16_f32 v49, v54, v55
	v_cvt_pk_bf16_f32 v50, v50, v51
	v_cvt_pk_bf16_f32 v51, v56, v57
	global_store_dwordx4 v[66:67], v[48:51], off offset:256
	s_nop 1
	v_ffbh_u32_e32 v50, v251
	v_min_u32_e32 v50, 32, v50
	v_lshlrev_b64 v[48:49], v50, v[250:251]
	v_min_u32_e32 v48, 1, v48
	v_or_b32_e32 v48, v49, v48
	v_cvt_f32_u32_e32 v48, v48
	v_sub_u32_e32 v49, 32, v50
	v_lshl_add_u64 v[50:51], v[140:141], 0, s[6:7]
	s_mov_b32 s6, 0x24000
	v_ldexp_f32 v48, v48, v49
	v_fmamk_f32 v48, v48, 0x2e000000, v191
	v_cmp_gt_f32_e32 vcc, s58, v48
	v_mul_f32_e32 v49, 0x4b800000, v48
	s_nop 0
	v_cndmask_b32_e32 v48, v48, v49, vcc
	v_rsq_f32_e32 v48, v48
	s_nop 0
	v_mul_f32_e32 v49, 0x45800000, v48
	v_cndmask_b32_e32 v48, v48, v49, vcc
	v_pk_mul_f32 v[44:45], v[44:45], v[48:49] op_sel_hi:[1,0]
	v_pk_mul_f32 v[46:47], v[46:47], v[48:49] op_sel_hi:[1,0]
	v_pk_mul_f32 v[52:53], v[42:43], v[48:49] op_sel_hi:[1,0]
	v_pk_mul_f32 v[42:43], v[40:41], v[48:49] op_sel_hi:[1,0]
	v_cvt_pk_bf16_f32 v40, v44, v45
	v_add_co_u32_e32 v44, vcc, s6, v140
	v_cvt_pk_bf16_f32 v41, v46, v47
	v_cvt_pk_bf16_f32 v42, v42, v43
	v_cvt_pk_bf16_f32 v43, v52, v53
	v_addc_co_u32_e32 v45, vcc, 0, v141, vcc
	global_store_dwordx4 v[44:45], v[40:43], off
	v_pk_mul_f32 v[38:39], v[38:39], v[48:49] op_sel_hi:[1,0]
	v_pk_mul_f32 v[36:37], v[36:37], v[48:49] op_sel_hi:[1,0]
	v_pk_mul_f32 v[40:41], v[34:35], v[48:49] op_sel_hi:[1,0]
	v_pk_mul_f32 v[34:35], v[32:33], v[48:49] op_sel_hi:[1,0]
	v_cvt_pk_bf16_f32 v32, v36, v37
	v_cvt_pk_bf16_f32 v33, v38, v39
	v_cvt_pk_bf16_f32 v34, v34, v35
	v_cvt_pk_bf16_f32 v35, v40, v41
	global_store_dwordx4 v[50:51], v[32:35], off offset:256
	s_mov_b64 s[6:7], 0x28000
	s_nop 1
	v_ffbh_u32_e32 v34, v253
	v_min_u32_e32 v34, 32, v34
	v_lshlrev_b64 v[32:33], v34, v[252:253]
	v_min_u32_e32 v32, 1, v32
	v_or_b32_e32 v32, v33, v32
	v_cvt_f32_u32_e32 v32, v32
	v_sub_u32_e32 v33, 32, v34
	v_lshl_add_u64 v[34:35], v[140:141], 0, s[6:7]
	s_mov_b32 s6, 0x28000
	v_ldexp_f32 v32, v32, v33
	v_fmamk_f32 v32, v32, 0x2e000000, v191
	v_cmp_gt_f32_e32 vcc, s58, v32
	v_mul_f32_e32 v33, 0x4b800000, v32
	s_nop 0
	v_cndmask_b32_e32 v32, v32, v33, vcc
	v_rsq_f32_e32 v32, v32
	s_nop 0
	v_mul_f32_e32 v33, 0x45800000, v32
	v_cndmask_b32_e32 v32, v32, v33, vcc
	v_pk_mul_f32 v[28:29], v[28:29], v[32:33] op_sel_hi:[1,0]
	v_pk_mul_f32 v[30:31], v[30:31], v[32:33] op_sel_hi:[1,0]
	v_pk_mul_f32 v[36:37], v[26:27], v[32:33] op_sel_hi:[1,0]
	v_pk_mul_f32 v[26:27], v[24:25], v[32:33] op_sel_hi:[1,0]
	v_cvt_pk_bf16_f32 v24, v28, v29
	v_add_co_u32_e32 v28, vcc, s6, v140
	v_cvt_pk_bf16_f32 v25, v30, v31
	v_cvt_pk_bf16_f32 v26, v26, v27
	v_cvt_pk_bf16_f32 v27, v36, v37
	v_addc_co_u32_e32 v29, vcc, 0, v141, vcc
	global_store_dwordx4 v[28:29], v[24:27], off
	v_pk_mul_f32 v[22:23], v[22:23], v[32:33] op_sel_hi:[1,0]
	v_pk_mul_f32 v[20:21], v[20:21], v[32:33] op_sel_hi:[1,0]
	v_pk_mul_f32 v[24:25], v[18:19], v[32:33] op_sel_hi:[1,0]
	v_pk_mul_f32 v[18:19], v[16:17], v[32:33] op_sel_hi:[1,0]
	v_cvt_pk_bf16_f32 v16, v20, v21
	v_cvt_pk_bf16_f32 v17, v22, v23
	v_cvt_pk_bf16_f32 v18, v18, v19
	v_cvt_pk_bf16_f32 v19, v24, v25
	global_store_dwordx4 v[34:35], v[16:19], off offset:256
	s_mov_b64 s[6:7], 0x2c000
	s_nop 1
	v_ffbh_u32_e32 v18, v255
	v_min_u32_e32 v18, 32, v18
	v_lshlrev_b64 v[16:17], v18, v[254:255]
	v_min_u32_e32 v16, 1, v16
	v_or_b32_e32 v16, v17, v16
	v_cvt_f32_u32_e32 v16, v16
	v_sub_u32_e32 v17, 32, v18
	v_lshl_add_u64 v[18:19], v[140:141], 0, s[6:7]
	s_mov_b32 s6, 0x2c000
	v_ldexp_f32 v16, v16, v17
	v_fmamk_f32 v16, v16, 0x2e000000, v191
	v_cmp_gt_f32_e32 vcc, s58, v16
	v_mul_f32_e32 v17, 0x4b800000, v16
	s_nop 0
	v_cndmask_b32_e32 v16, v16, v17, vcc
	v_rsq_f32_e32 v16, v16
	s_nop 0
	v_mul_f32_e32 v17, 0x45800000, v16
	v_cndmask_b32_e32 v16, v16, v17, vcc
	v_pk_mul_f32 v[12:13], v[12:13], v[16:17] op_sel_hi:[1,0]
	v_pk_mul_f32 v[14:15], v[14:15], v[16:17] op_sel_hi:[1,0]
	v_pk_mul_f32 v[20:21], v[10:11], v[16:17] op_sel_hi:[1,0]
	v_pk_mul_f32 v[10:11], v[8:9], v[16:17] op_sel_hi:[1,0]
	v_cvt_pk_bf16_f32 v8, v12, v13
	v_add_co_u32_e32 v12, vcc, s6, v140
	v_cvt_pk_bf16_f32 v9, v14, v15
	v_cvt_pk_bf16_f32 v10, v10, v11
	v_cvt_pk_bf16_f32 v11, v20, v21
	v_addc_co_u32_e32 v13, vcc, 0, v141, vcc
	global_store_dwordx4 v[12:13], v[8:11], off
	v_pk_mul_f32 v[6:7], v[6:7], v[16:17] op_sel_hi:[1,0]
	v_pk_mul_f32 v[4:5], v[4:5], v[16:17] op_sel_hi:[1,0]
	v_pk_mul_f32 v[8:9], v[2:3], v[16:17] op_sel_hi:[1,0]
	v_pk_mul_f32 v[2:3], v[0:1], v[16:17] op_sel_hi:[1,0]
	v_cvt_pk_bf16_f32 v0, v4, v5
	v_cvt_pk_bf16_f32 v1, v6, v7
	v_cvt_pk_bf16_f32 v2, v2, v3
	v_cvt_pk_bf16_f32 v3, v8, v9
	s_mov_b64 s[6:7], -1
	s_andn2_b64 vcc, exec, s[38:39]
	global_store_dwordx4 v[18:19], v[0:3], off offset:256
	s_cbranch_vccnz .LBB0_1140
	s_andn2_b64 vcc, exec, s[4:5]
	s_cbranch_vccnz .LBB0_1139
	s_barrier
	s_branch .LBB0_1139
